# P5 tile prologue: the deferred (hook) stores of the previous tile are plain write-back stores (their acks sit on the prologue's wait), the epilogue / final-flush stores stay write-through; per-wave ho
# speedup vs baseline: 1.0048x; 1.0048x over previous
.LBB0_159:
	s_cmp_eq_u32 s75, 7
	s_cbranch_scc1 .Lp5_hook_w7
	s_waitcnt vmcnt(6)
	s_branch .Lp5_hook_wd
.Lp5_hook_w7:
	s_waitcnt vmcnt(10)
.Lp5_hook_wd:
	s_barrier
